# kv2-done counter sampled once at the start of the retention-output phase so the knorm wait usually skips its poll round trip
# baseline (speedup 1.0000x reference)
.LBB0_592:
	v_readlane_b32 s0, v254, 62
	v_readlane_b32 s1, v254, 63
	s_andn2_b64 vcc, exec, s[0:1]
	s_waitcnt lgkmcnt(0)
	v_cndmask_b32_e64 v0, 0, 1, s[0:1]
	v_cmp_ne_u32_e64 s[4:5], 1, v0
	s_barrier
	v_mbcnt_lo_u32_b32 v152, -1, 0
	v_mbcnt_hi_u32_b32 v152, -1, v152
	s_cmp_lg_u32 s98, 0
	s_cbranch_scc0 .Lkn_nopf
	v_readlane_b32 s99, v254, 25
	s_nop 3
	s_cmp_lg_u32 s99, 0
	s_cbranch_scc1 .Lkn_nopf
	s_mov_b64 s[100:101], exec
	s_mov_b64 exec, 1
	v_mov_b32_e32 v252, 0xfa0f200
	global_load_dword v252, v252, s[74:75] sc1
	s_mov_b64 exec, s[100:101]
.Lkn_nopf:
	s_cbranch_vccnz .LBB0_598
	v_lshlrev_b32_e32 v7, 4, v152
	v_readlane_b32 s6, v254, 45
	v_and_b32_e32 v128, 0x70, v7
	v_mov_b32_e32 v129, 0
	v_readlane_b32 s7, v254, 46
	v_and_b32_e32 v0, 0xf0, v7
	v_mov_b32_e32 v1, v129
	v_lshl_add_u64 v[130:131], s[6:7], 0, v[128:129]
	v_readlane_b32 s6, v255, 0
	v_readlane_b32 s7, v255, 1
	v_lshrrev_b32_e32 v10, 1, v152
	v_and_b32_e32 v6, 31, v152
	v_lshl_add_u64 v[132:133], s[6:7], 0, v[0:1]
	v_lshlrev_b32_e32 v0, 1, v152
	v_and_b32_e32 v12, 19, v152
	v_and_b32_e32 v13, 8, v0
	v_and_b32_e32 v14, 4, v10
	v_ashrrev_i32_e32 v153, 5, v152
	v_readlane_b32 s0, v254, 48
	v_or_b32_e32 v134, s42, v6
	v_or3_b32 v0, v14, v12, v13
	s_lshl_b32 s0, s0, 16
	v_lshrrev_b32_e32 v15, 1, v0
	v_lshlrev_b32_e32 v0, 3, v153
	v_add_u32_e32 v1, 1, v134
	s_add_i32 s1, s0, 0
	v_readlane_b32 s2, v254, 52
	v_cvt_f32_ubyte0_e32 v157, v1
	v_ashrrev_i32_e32 v1, 31, v0
	v_readlane_b32 s7, v254, 53
	v_lshl_add_u32 v3, s2, 6, v152
	s_movk_i32 s3, 0x70
	v_bfe_u32 v11, v152, 1, 3
	v_lshl_add_u64 v[4:5], v[0:1], 2, s[8:9]
	s_add_i32 s2, s1, s7
	v_lshlrev_b32_e32 v1, 7, v6
	v_bitop3_b32 v8, v3, s3, v7 bitop3:0x48
	v_lshlrev_b32_e32 v2, 8, v6
	v_add3_u32 v159, s2, v1, v0
	v_lshlrev_b32_e32 v160, 4, v11
	v_ashrrev_i32_e32 v136, 3, v3
	v_ashrrev_i32_e32 v161, 4, v3
	v_add_u32_e32 v1, 0x100, v3
	v_add_u32_e32 v6, 0x200, v3
	v_add_u32_e32 v11, 0x300, v3
	v_lshlrev_b32_e32 v3, 4, v3
	s_movk_i32 s6, 0xff80
	v_and_or_b32 v17, v3, s6, v8
	v_xor_b32_e32 v3, v161, v152
	v_ashrrev_i32_e32 v162, 4, v1
	v_lshlrev_b32_e32 v3, 4, v3
	v_and_b32_e32 v19, 0xf0, v3
	v_xor_b32_e32 v3, v162, v152
	v_lshlrev_b32_e32 v3, 4, v3
	v_ashrrev_i32_e32 v163, 4, v6
	v_and_b32_e32 v21, 0xf0, v3
	v_lshlrev_b32_e32 v3, 4, v6
	v_ashrrev_i32_e32 v140, 3, v6
	v_and_or_b32 v6, v3, s6, v8
	v_xor_b32_e32 v3, v163, v152
	v_lshlrev_b32_e32 v3, 4, v3
	v_ashrrev_i32_e32 v138, 3, v1
	v_ashrrev_i32_e32 v164, 4, v11
	v_lshlrev_b32_e32 v1, 4, v1
	v_and_b32_e32 v23, 0xf0, v3
	v_lshlrev_b32_e32 v3, 4, v11
	v_and_or_b32 v1, v1, s6, v8
	v_and_or_b32 v8, v3, s6, v8
	v_xor_b32_e32 v3, v164, v152
	v_lshlrev_b32_e32 v3, 4, v3
	v_add_u32_e32 v16, 2, v153
	v_and_b32_e32 v24, 0xf0, v3
	v_bitop3_b32 v3, v10, v153, 7 bitop3:0x6c
	v_lshlrev_b32_e32 v25, 4, v3
	v_bitop3_b32 v3, v16, v10, 7 bitop3:0x78
	v_lshlrev_b32_e32 v26, 4, v3
	v_add_u32_e32 v3, 4, v153
	v_bitop3_b32 v27, v3, v10, 7 bitop3:0x78
	v_add_u32_e32 v28, 6, v153
	v_bitop3_b32 v3, v15, v3, 7 bitop3:0x6c
	v_lshlrev_b32_e32 v30, 4, v3
	v_bitop3_b32 v3, v15, v28, 7 bitop3:0x6c
	v_bitop3_b32 v29, v15, v153, 7 bitop3:0x6c
	v_bitop3_b32 v16, v15, v16, 7 bitop3:0x6c
	v_lshlrev_b32_e32 v15, 4, v3
	v_mov_b32_e32 v3, 0x70
	s_movk_i32 s6, 0x50
	v_bitop3_b32 v38, v7, s6, v3 bitop3:0x6c
	s_movk_i32 s6, 0x60
	v_bitop3_b32 v31, v7, 16, v3 bitop3:0x6c
	v_bitop3_b32 v33, v7, 32, v3 bitop3:0x6c
	v_bitop3_b32 v35, v7, 48, v3 bitop3:0x6c
	v_bitop3_b32 v36, v7, 64, v3 bitop3:0x6c
	v_bitop3_b32 v40, v7, s6, v3 bitop3:0x6c
	v_mov_b32_e32 v3, v129
	v_add_u32_e32 v155, s1, v2
	v_lshl_add_u64 v[150:151], v[4:5], 0, v[2:3]
	v_or3_b32 v2, v12, v13, v14
	v_lshl_or_b32 v2, v2, 7, s0
	v_add3_u32 v3, v2, v15, 0
	v_lshl_add_u32 v9, v134, 7, s1
	v_bitop3_b32 v10, v28, v10, 7 bitop3:0x78
	v_lshlrev_b32_e32 v29, 4, v29
	v_lshlrev_b32_e32 v16, 4, v16
	v_add_u32_e32 v165, 0x4000, v3
	v_add3_u32 v3, v2, v30, 0
	s_mov_b32 s61, 0
	v_sub_u32_e32 v154, 0, v0
	v_add_u32_e32 v158, v9, v0
	v_xor_b32_e32 v0, 64, v160
	v_ashrrev_i32_e32 v142, 3, v11
	v_lshl_add_u32 v18, v161, 8, s1
	v_lshl_add_u32 v20, v162, 8, s1
	v_lshl_add_u32 v22, v163, 8, s1
	v_lshl_add_u32 v11, v164, 8, s1
	v_lshlrev_b32_e32 v27, 4, v27
	v_lshlrev_b32_e32 v10, 4, v10
	v_xor_b32_e32 v28, 16, v160
	v_xor_b32_e32 v32, 32, v160
	v_xor_b32_e32 v34, 48, v160
	v_xor_b32_e32 v37, 0x50, v160
	v_xor_b32_e32 v39, 0x60, v160
	v_xor_b32_e32 v41, 0x70, v160
	v_bitop3_b32 v7, v7, s3, v7 bitop3:0xc
	v_add_u32_e32 v166, 0x4000, v3
	v_add3_u32 v3, v2, v16, 0
	v_add3_u32 v2, v2, v29, 0
	v_and_b32_e32 v156, 15, v152
	s_mov_b32 s43, s61
	v_ashrrev_i32_e32 v137, 31, v136
	v_ashrrev_i32_e32 v139, 31, v138
	v_ashrrev_i32_e32 v141, 31, v140
	v_ashrrev_i32_e32 v143, 31, v142
	v_add_u32_e32 v135, -1, v134
	v_add_u32_e32 v145, -3, v134
	v_add_u32_e32 v144, -2, v134
	v_add_u32_e32 v147, -5, v134
	v_add_u32_e32 v146, -4, v134
	v_add_u32_e32 v149, -7, v134
	v_add_u32_e32 v148, -6, v134
	s_add_i32 s3, s7, 0x1000
	v_add_u32_e32 v167, 0x4000, v3
	v_add_u32_e32 v168, 0x4000, v2
	s_mov_b32 s10, 0xc2fc0000
	v_mov_b32_e32 v169, 0x3ecc95a3
	s_movk_i32 s11, 0x1400
	v_add_u32_e32 v170, s1, v17
	v_add_u32_e32 v171, v18, v19
	v_add_u32_e32 v172, s1, v1
	v_add_u32_e32 v173, v20, v21
	v_add_u32_e32 v174, s1, v6
	v_add_u32_e32 v175, v22, v23
	v_add_u32_e32 v176, s1, v8
	v_add_u32_e32 v177, v11, v24
	v_add_u32_e32 v178, v9, v25
	v_add_u32_e32 v179, v9, v26
	v_add_u32_e32 v180, v9, v27
	v_add_u32_e32 v181, v9, v10
	s_mov_b32 s20, 0x5040100
	s_mov_b64 s[62:63], 0x2040
	s_mov_b64 s[64:65], 0x2080
	s_mov_b64 s[66:67], 0x20c0
	v_add_u32_e32 v182, v158, v28
	v_add_u32_e32 v183, v158, v32
	v_add_u32_e32 v184, v158, v34
	v_add_u32_e32 v185, v158, v0
	v_add_u32_e32 v186, v158, v37
	v_add_u32_e32 v187, v158, v39
	v_add_u32_e32 v188, v158, v41
	v_mov_b32_e32 v189, 0x358637bd
	s_mov_b32 s21, 0x800000
	v_add_u32_e32 v190, v159, v31
	v_add_u32_e32 v191, v159, v33
	v_add_u32_e32 v192, v159, v35
	v_add_u32_e32 v193, v159, v36
	v_add_u32_e32 v194, v159, v38
	v_add_u32_e32 v195, v159, v40
	v_add_u32_e32 v196, v159, v7
	v_mov_b32_e32 v197, 0x42800000
	v_mov_b32_e32 v198, 0x7fc00000
	v_mov_b32_e32 v199, 0xff800000
	v_not_b32_e32 v200, 63
	s_mov_b32 s33, s70
	s_mov_b32 s101, s78
	s_cmp_lg_u32 s98, 0
	s_cbranch_scc0 .Lro_nodeal
	s_and_b32 s99, s70, 7
	s_lshr_b32 s100, s70, 3
	s_lshr_b32 s33, s99, 2
	s_lshl_b32 s33, s33, 3
	s_lshr_b32 s101, s100, 2
	s_or_b32 s33, s33, s101
	s_lshl_b32 s33, s33, 5
	s_and_b32 s99, s99, 3
	s_lshl_b32 s99, s99, 3
	s_or_b32 s33, s33, s99
	s_and_b32 s100, s100, 3
	s_lshl_b32 s100, s100, 1
	s_or_b32 s33, s33, s100
	s_mov_b32 s101, 1

.LBB0_598:
	s_cmp_lg_u32 s98, 0
	s_cbranch_scc0 .Lkn_nowait
	v_readlane_b32 s99, v254, 25
	s_nop 3
	s_cmp_lg_u32 s99, 0
	s_cbranch_scc1 .Lkn_nowait
	s_mov_b64 s[100:101], exec
	s_mov_b64 exec, 1
	v_mov_b32_e32 v0, 0x21004
	ds_read_b32 v1, v0
	v_mov_b32_e32 v0, 0xfa0f200
	s_mov_b32 s99, 0
	s_waitcnt lgkmcnt(0)
	s_waitcnt vmcnt(0)
	v_cmp_ge_u32_e32 vcc, v252, v1
	s_cbranch_vccnz .Lkn_done
